# natten relative-position-bias table load: all loads of a thread issued together (was two per trip with a wait)
# speedup vs baseline: 1.0032x; 1.0010x over previous
.LBB0_387:
	s_mov_b32 s2, s83
	s_mov_b64 s[0:1], 0
	v_mov_b32_e32 v2, v192
	s_movk_i32 s4, 0xe88
	s_barrier
	s_nop 0
	v_cmp_gt_i32_e32 vcc, s4, v2
	s_and_saveexec_b64 s[4:5], vcc
	s_cbranch_execz .LBB0_395
	s_mul_i32 s6, s2, 0xe88
	v_add_u32_e32 v3, s6, v2
	v_lshlrev_b32_e32 v3, 2, v3
	v_lshlrev_b32_e32 v7, 2, v2
	v_add_u32_e32 v7, 0x14000, v7
	global_load_dword v10, v3, s[74:75]
	v_add_u32_e32 v4, 0x800, v3
	global_load_dword v11, v4, s[74:75]
	v_add_u32_e32 v4, 0x1000, v3
	global_load_dword v12, v4, s[74:75]
	v_add_u32_e32 v4, 0x1800, v3
	global_load_dword v13, v4, s[74:75]
	v_add_u32_e32 v4, 0x2000, v3
	global_load_dword v14, v4, s[74:75]
	v_add_u32_e32 v4, 0x2800, v3
	global_load_dword v15, v4, s[74:75]
	v_add_u32_e32 v4, 0x3000, v3
	global_load_dword v16, v4, s[74:75]
	v_add_u32_e32 v4, 0x3800, v3
	v_cmp_gt_u32_e32 vcc, 136, v2
	s_and_saveexec_b64 s[36:37], vcc
	global_load_dword v17, v4, s[74:75]
	s_mov_b64 exec, s[36:37]
	s_waitcnt vmcnt(0)
	ds_write_b32 v7, v10
	ds_write_b32 v7, v11 offset:2048
	ds_write_b32 v7, v12 offset:4096
	ds_write_b32 v7, v13 offset:6144
	ds_write_b32 v7, v14 offset:8192
	ds_write_b32 v7, v15 offset:10240
	ds_write_b32 v7, v16 offset:12288
	s_and_saveexec_b64 s[36:37], vcc
	s_waitcnt vmcnt(0)
	ds_write_b32 v7, v17 offset:14336
	s_mov_b64 exec, s[36:37]
